# attention softmax: per-tile max tree replaced by post-hoc row-sum check (sum<=256), QK recompute on the rare path
# speedup vs baseline: 1.0052x; 1.0052x over previous
.Lat_entry:
	s_mov_b32 s92, m0
	s_add_i32 s71, s97, 0x10000
	s_mov_b32 s70, 0
	s_movk_i32 s81, 0x7f
	s_mov_b32 s80, 0x20000
	s_add_i32 s51, s90, 0x80000
	s_add_u32 s50, s62, s51
	s_addc_u32 s51, s63, 0
	s_mov_b32 s84, 1
	s_mov_b32 s94, 0xff800000
	v_mov_b32_e32 v246, 0
	v_mov_b32_e32 v247, 0
	v_mov_b32_e32 v248, 0
	v_mov_b32_e32 v249, 0
	v_mov_b32_e32 v250, 0
	v_mov_b32_e32 v251, 0
	v_mov_b32_e32 v252, 0
	v_mov_b32_e32 v253, 0
	v_readlane_b32 s4, v254, 24
	v_and_b32_e32 v234, 15, v211
	v_lshrrev_b32_e32 v235, 4, v211
	v_xor_b32_e32 v236, v234, v235
	v_lshlrev_b32_e32 v236, 4, v236
	v_lshl_add_u32 v236, v234, 8, v236
	v_add_u32_e32 v221, s4, v236
	v_lshlrev_b32_e32 v237, 2, v235
	v_sub_u32_e32 v237, v234, v237
	v_add_u32_e32 v223, s3, v237
	v_bfe_u32 v237, v211, 5, 1
	v_lshlrev_b32_e32 v237, 12, v237
	v_bfe_u32 v238, v211, 4, 1
	v_lshl_add_u32 v237, v238, 7, v237
	v_bfe_u32 v238, v211, 2, 2
	v_lshl_add_u32 v237, v238, 5, v237
	v_and_b32_e32 v238, 3, v211
	v_lshl_add_u32 v237, v238, 3, v237
	v_add_u32_e32 v222, 0x8000, v237
	v_mov_b32_e32 v243, v233
	v_mov_b32_e32 v244, 0
	v_xor_b32_e32 v234, s70, v221
	v_xor_b32_e32 v235, 64, v234
	v_xor_b32_e32 v236, 0x80, v234
	v_xor_b32_e32 v237, 0xc0, v234

.Lat_dt_a:
	s_add_i32 s4, s91, 0xb0
	s_cmp_le_u32 s4, s3
	s_cbranch_scc0 .Lat_diag_a
.Lat_sm_a:
	s_cmp_lg_u32 s84, 0
	s_cbranch_scc1 .Lat_max_a
.Lat_exp_a:
	v_exp_f32_e32 v130, v130
	v_exp_f32_e32 v131, v131
	v_exp_f32_e32 v132, v132
	v_add_f32_e32 v0, v130, v131
	v_exp_f32_e32 v133, v133
	v_add_f32_e32 v0, v0, v132
	v_exp_f32_e32 v134, v134
	v_add_f32_e32 v0, v0, v133
	v_exp_f32_e32 v135, v135
	v_add_f32_e32 v0, v0, v134
	v_exp_f32_e32 v136, v136
	v_add_f32_e32 v0, v0, v135
	v_exp_f32_e32 v137, v137
	v_add_f32_e32 v0, v0, v136
	v_exp_f32_e32 v138, v138
	v_add_f32_e32 v0, v0, v137
	v_exp_f32_e32 v139, v139
	v_add_f32_e32 v0, v0, v138
	v_exp_f32_e32 v140, v140
	v_add_f32_e32 v0, v0, v139
	v_exp_f32_e32 v141, v141
	v_add_f32_e32 v0, v0, v140
	v_exp_f32_e32 v142, v142
	v_add_f32_e32 v0, v0, v141
	v_exp_f32_e32 v143, v143
	v_add_f32_e32 v0, v0, v142
	v_exp_f32_e32 v144, v144
	v_add_f32_e32 v0, v0, v143
	v_exp_f32_e32 v145, v145
	v_add_f32_e32 v0, v0, v144
	v_exp_f32_e32 v146, v146
	v_exp_f32_e32 v147, v147
	v_exp_f32_e32 v148, v148
	v_add_f32_e32 v233, v146, v147
	v_exp_f32_e32 v149, v149
	v_add_f32_e32 v233, v233, v148
	v_exp_f32_e32 v150, v150
	v_add_f32_e32 v233, v233, v149
	v_exp_f32_e32 v151, v151
	v_add_f32_e32 v233, v233, v150
	v_exp_f32_e32 v152, v152
	v_add_f32_e32 v233, v233, v151
	v_exp_f32_e32 v153, v153
	v_add_f32_e32 v233, v233, v152
	v_exp_f32_e32 v154, v154
	v_add_f32_e32 v233, v233, v153
	v_exp_f32_e32 v155, v155
	v_add_f32_e32 v233, v233, v154
	v_exp_f32_e32 v156, v156
	v_add_f32_e32 v233, v233, v155
	v_exp_f32_e32 v157, v157
	v_add_f32_e32 v233, v233, v156
	v_exp_f32_e32 v158, v158
	v_add_f32_e32 v233, v233, v157
	v_exp_f32_e32 v159, v159
	v_add_f32_e32 v233, v233, v158
	v_exp_f32_e32 v160, v160
	v_add_f32_e32 v233, v233, v159
	v_exp_f32_e32 v161, v161
	v_add_f32_e32 v233, v233, v160
	v_add_f32_e32 v0, v0, v145
	v_add_f32_e32 v233, v233, v161
	v_max_f32_e32 v238, v0, v233
	v_cmp_ge_f32_e32 vcc, 0x43800000, v238
	s_cmp_eq_u64 vcc, exec
	s_cbranch_scc0 .Lat_redo_a
	v_add_f32_e32 v232, v232, v0
	v_cvt_pk_bf16_f32 v130, v130, v131
	v_cvt_pk_bf16_f32 v131, v132, v133
	v_cvt_pk_bf16_f32 v132, v134, v135
	v_cvt_pk_bf16_f32 v133, v136, v137
	v_cvt_pk_bf16_f32 v134, v138, v139
	v_cvt_pk_bf16_f32 v135, v140, v141
	v_cvt_pk_bf16_f32 v136, v142, v143
	v_cvt_pk_bf16_f32 v137, v144, v145
	v_add_f32_e32 v244, v244, v233
	v_cvt_pk_bf16_f32 v146, v146, v147
	v_cvt_pk_bf16_f32 v147, v148, v149
	v_cvt_pk_bf16_f32 v148, v150, v151
	v_cvt_pk_bf16_f32 v149, v152, v153
	v_cvt_pk_bf16_f32 v150, v154, v155
	v_cvt_pk_bf16_f32 v151, v156, v157
	v_cvt_pk_bf16_f32 v152, v158, v159
	v_cvt_pk_bf16_f32 v153, v160, v161
	s_waitcnt lgkmcnt(4)
	v_mfma_f32_16x16x32_bf16 v[114:117], v[162:165], v[130:133], v[114:117]
	v_mfma_f32_16x16x32_bf16 v[122:125], v[162:165], v[146:149], v[122:125]
	ds_read_b64_tr_b16 v[162:163], v242 offset:512
	ds_read_b64_tr_b16 v[164:165], v242 offset:8704
	v_mfma_f32_16x16x32_bf16 v[114:117], v[166:169], v[134:137], v[114:117]
	v_mfma_f32_16x16x32_bf16 v[122:125], v[166:169], v[150:153], v[122:125]
	ds_read_b64_tr_b16 v[166:167], v242 offset:16896
	ds_read_b64_tr_b16 v[168:169], v242 offset:25088
	s_waitcnt lgkmcnt(4)
	v_mfma_f32_16x16x32_bf16 v[118:121], v[170:173], v[130:133], v[118:121]
	v_mfma_f32_16x16x32_bf16 v[126:129], v[170:173], v[146:149], v[126:129]
	ds_read_b64_tr_b16 v[170:171], v242 offset:768
	ds_read_b64_tr_b16 v[172:173], v242 offset:8960
	v_mfma_f32_16x16x32_bf16 v[118:121], v[174:177], v[134:137], v[118:121]
	v_mfma_f32_16x16x32_bf16 v[126:129], v[174:177], v[150:153], v[126:129]
	ds_read_b64_tr_b16 v[174:175], v242 offset:17152
	ds_read_b64_tr_b16 v[176:177], v242 offset:25344
	s_waitcnt lgkmcnt(4)
	v_mfma_f32_16x16x32_bf16 v[98:101], v[162:165], v[130:133], v[98:101]
	v_mfma_f32_16x16x32_bf16 v[106:109], v[162:165], v[146:149], v[106:109]
	ds_read_b64_tr_b16 v[162:163], v242 offset:1024
	ds_read_b64_tr_b16 v[164:165], v242 offset:9216
	v_mfma_f32_16x16x32_bf16 v[98:101], v[166:169], v[134:137], v[98:101]
	v_mfma_f32_16x16x32_bf16 v[106:109], v[166:169], v[150:153], v[106:109]
	ds_read_b64_tr_b16 v[166:167], v242 offset:17408
	ds_read_b64_tr_b16 v[168:169], v242 offset:25600
	s_waitcnt lgkmcnt(4)
	v_mfma_f32_16x16x32_bf16 v[102:105], v[170:173], v[130:133], v[102:105]
	v_mfma_f32_16x16x32_bf16 v[110:113], v[170:173], v[146:149], v[110:113]
	ds_read_b64_tr_b16 v[170:171], v242 offset:1280
	ds_read_b64_tr_b16 v[172:173], v242 offset:9472
	v_mfma_f32_16x16x32_bf16 v[102:105], v[174:177], v[134:137], v[102:105]
	v_mfma_f32_16x16x32_bf16 v[110:113], v[174:177], v[150:153], v[110:113]
	ds_read_b64_tr_b16 v[174:175], v242 offset:17664
	ds_read_b64_tr_b16 v[176:177], v242 offset:25856
	s_waitcnt lgkmcnt(4)
	v_mfma_f32_16x16x32_bf16 v[82:85], v[162:165], v[130:133], v[82:85]
	v_mfma_f32_16x16x32_bf16 v[90:93], v[162:165], v[146:149], v[90:93]
	ds_read_b64_tr_b16 v[162:163], v242 offset:1536
	ds_read_b64_tr_b16 v[164:165], v242 offset:9728
	v_mfma_f32_16x16x32_bf16 v[82:85], v[166:169], v[134:137], v[82:85]
	v_mfma_f32_16x16x32_bf16 v[90:93], v[166:169], v[150:153], v[90:93]
	ds_read_b64_tr_b16 v[166:167], v242 offset:17920
	ds_read_b64_tr_b16 v[168:169], v242 offset:26112
	s_waitcnt lgkmcnt(4)
	v_mfma_f32_16x16x32_bf16 v[86:89], v[170:173], v[130:133], v[86:89]
	v_mfma_f32_16x16x32_bf16 v[94:97], v[170:173], v[146:149], v[94:97]
	ds_read_b64_tr_b16 v[170:171], v242 offset:1792
	ds_read_b64_tr_b16 v[172:173], v242 offset:9984
	v_mfma_f32_16x16x32_bf16 v[86:89], v[174:177], v[134:137], v[86:89]
	v_mfma_f32_16x16x32_bf16 v[94:97], v[174:177], v[150:153], v[94:97]
	ds_read_b64_tr_b16 v[174:175], v242 offset:18176
	ds_read_b64_tr_b16 v[176:177], v242 offset:26368
	s_waitcnt lgkmcnt(4)
	v_mfma_f32_16x16x32_bf16 v[66:69], v[162:165], v[130:133], v[66:69]
	v_mfma_f32_16x16x32_bf16 v[74:77], v[162:165], v[146:149], v[74:77]
	ds_read_b64_tr_b16 v[162:163], v242 offset:2048
	ds_read_b64_tr_b16 v[164:165], v242 offset:10240
	v_mfma_f32_16x16x32_bf16 v[66:69], v[166:169], v[134:137], v[66:69]
	v_mfma_f32_16x16x32_bf16 v[74:77], v[166:169], v[150:153], v[74:77]
	ds_read_b64_tr_b16 v[166:167], v242 offset:18432
	ds_read_b64_tr_b16 v[168:169], v242 offset:26624
	s_waitcnt lgkmcnt(4)
	v_mfma_f32_16x16x32_bf16 v[70:73], v[170:173], v[130:133], v[70:73]
	v_mfma_f32_16x16x32_bf16 v[78:81], v[170:173], v[146:149], v[78:81]
	ds_read_b64_tr_b16 v[170:171], v242 offset:2304
	ds_read_b64_tr_b16 v[172:173], v242 offset:10496
	v_mfma_f32_16x16x32_bf16 v[70:73], v[174:177], v[134:137], v[70:73]
	v_mfma_f32_16x16x32_bf16 v[78:81], v[174:177], v[150:153], v[78:81]
	ds_read_b64_tr_b16 v[174:175], v242 offset:18688
	ds_read_b64_tr_b16 v[176:177], v242 offset:26880
	s_waitcnt lgkmcnt(4)
	v_mfma_f32_16x16x32_bf16 v[50:53], v[162:165], v[130:133], v[50:53]
	v_mfma_f32_16x16x32_bf16 v[58:61], v[162:165], v[146:149], v[58:61]
	ds_read_b64_tr_b16 v[162:163], v242 offset:2560
	ds_read_b64_tr_b16 v[164:165], v242 offset:10752
	v_mfma_f32_16x16x32_bf16 v[50:53], v[166:169], v[134:137], v[50:53]
	v_mfma_f32_16x16x32_bf16 v[58:61], v[166:169], v[150:153], v[58:61]
	ds_read_b64_tr_b16 v[166:167], v242 offset:18944
	ds_read_b64_tr_b16 v[168:169], v242 offset:27136
	s_waitcnt lgkmcnt(4)
	v_mfma_f32_16x16x32_bf16 v[54:57], v[170:173], v[130:133], v[54:57]
	v_mfma_f32_16x16x32_bf16 v[62:65], v[170:173], v[146:149], v[62:65]
	ds_read_b64_tr_b16 v[170:171], v242 offset:2816
	ds_read_b64_tr_b16 v[172:173], v242 offset:11008
	v_mfma_f32_16x16x32_bf16 v[54:57], v[174:177], v[134:137], v[54:57]
	v_mfma_f32_16x16x32_bf16 v[62:65], v[174:177], v[150:153], v[62:65]
	ds_read_b64_tr_b16 v[174:175], v242 offset:19200
	ds_read_b64_tr_b16 v[176:177], v242 offset:27392
	s_waitcnt lgkmcnt(4)
	v_mfma_f32_16x16x32_bf16 v[34:37], v[162:165], v[130:133], v[34:37]
	v_mfma_f32_16x16x32_bf16 v[42:45], v[162:165], v[146:149], v[42:45]
	ds_read_b64_tr_b16 v[162:163], v242 offset:3072
	ds_read_b64_tr_b16 v[164:165], v242 offset:11264
	v_mfma_f32_16x16x32_bf16 v[34:37], v[166:169], v[134:137], v[34:37]
	v_mfma_f32_16x16x32_bf16 v[42:45], v[166:169], v[150:153], v[42:45]
	ds_read_b64_tr_b16 v[166:167], v242 offset:19456
	ds_read_b64_tr_b16 v[168:169], v242 offset:27648
	s_waitcnt lgkmcnt(4)
	v_mfma_f32_16x16x32_bf16 v[38:41], v[170:173], v[130:133], v[38:41]
	v_mfma_f32_16x16x32_bf16 v[46:49], v[170:173], v[146:149], v[46:49]
	ds_read_b64_tr_b16 v[170:171], v242 offset:3328
	ds_read_b64_tr_b16 v[172:173], v242 offset:11520
	v_mfma_f32_16x16x32_bf16 v[38:41], v[174:177], v[134:137], v[38:41]
	v_mfma_f32_16x16x32_bf16 v[46:49], v[174:177], v[150:153], v[46:49]
	ds_read_b64_tr_b16 v[174:175], v242 offset:19712
	ds_read_b64_tr_b16 v[176:177], v242 offset:27904
	s_waitcnt lgkmcnt(4)
	v_mfma_f32_16x16x32_bf16 v[18:21], v[162:165], v[130:133], v[18:21]
	v_mfma_f32_16x16x32_bf16 v[26:29], v[162:165], v[146:149], v[26:29]
	ds_read_b64_tr_b16 v[162:163], v242 offset:3584
	ds_read_b64_tr_b16 v[164:165], v242 offset:11776
	v_mfma_f32_16x16x32_bf16 v[18:21], v[166:169], v[134:137], v[18:21]
	v_mfma_f32_16x16x32_bf16 v[26:29], v[166:169], v[150:153], v[26:29]
	ds_read_b64_tr_b16 v[166:167], v242 offset:19968
	ds_read_b64_tr_b16 v[168:169], v242 offset:28160
	s_waitcnt lgkmcnt(4)
	v_mfma_f32_16x16x32_bf16 v[22:25], v[170:173], v[130:133], v[22:25]
	v_mfma_f32_16x16x32_bf16 v[30:33], v[170:173], v[146:149], v[30:33]
	ds_read_b64_tr_b16 v[170:171], v242 offset:3840
	ds_read_b64_tr_b16 v[172:173], v242 offset:12032
	v_mfma_f32_16x16x32_bf16 v[22:25], v[174:177], v[134:137], v[22:25]
	v_mfma_f32_16x16x32_bf16 v[30:33], v[174:177], v[150:153], v[30:33]
	ds_read_b64_tr_b16 v[174:175], v242 offset:20224
	ds_read_b64_tr_b16 v[176:177], v242 offset:28416
	s_waitcnt lgkmcnt(4)
	v_mfma_f32_16x16x32_bf16 v[2:5], v[162:165], v[130:133], v[2:5]
	v_mfma_f32_16x16x32_bf16 v[10:13], v[162:165], v[146:149], v[10:13]
	v_mfma_f32_16x16x32_bf16 v[2:5], v[166:169], v[134:137], v[2:5]
	v_mfma_f32_16x16x32_bf16 v[10:13], v[166:169], v[150:153], v[10:13]
	s_waitcnt lgkmcnt(0)
	v_mfma_f32_16x16x32_bf16 v[6:9], v[170:173], v[130:133], v[6:9]
	v_mfma_f32_16x16x32_bf16 v[14:17], v[170:173], v[146:149], v[14:17]
	v_mfma_f32_16x16x32_bf16 v[6:9], v[174:177], v[134:137], v[6:9]
	v_mfma_f32_16x16x32_bf16 v[14:17], v[174:177], v[150:153], v[14:17]
	s_xor_b32 s4, s70, 0x10000
	v_xor_b32_e32 v234, s4, v221
	v_xor_b32_e32 v235, 64, v234
	v_xor_b32_e32 v236, 0x80, v234
	v_xor_b32_e32 v237, 0xc0, v234
	s_branch .Lat_end_a
.Lat_redo_a:
	s_mov_b32 s84, 1
	s_waitcnt lgkmcnt(0)
	v_xor_b32_e32 v234, s70, v221
	v_xor_b32_e32 v235, 64, v234
	v_xor_b32_e32 v236, 0x80, v234
	v_xor_b32_e32 v237, 0xc0, v234
	ds_read_b128 v[162:165], v234
	s_waitcnt lgkmcnt(0)
	v_mfma_f32_16x16x32_bf16 v[130:133], v[162:165], v[178:181], v[246:249]
	v_mfma_f32_16x16x32_bf16 v[146:149], v[162:165], v[194:197], v[250:253]
	ds_read_b128 v[162:165], v235
	s_waitcnt lgkmcnt(0)
	v_mfma_f32_16x16x32_bf16 v[130:133], v[162:165], v[182:185], v[130:133]
	v_mfma_f32_16x16x32_bf16 v[146:149], v[162:165], v[198:201], v[146:149]
	ds_read_b128 v[162:165], v236
	s_waitcnt lgkmcnt(0)
	v_mfma_f32_16x16x32_bf16 v[130:133], v[162:165], v[186:189], v[130:133]
	v_mfma_f32_16x16x32_bf16 v[146:149], v[162:165], v[202:205], v[146:149]
	ds_read_b128 v[162:165], v237
	s_waitcnt lgkmcnt(0)
	v_mfma_f32_16x16x32_bf16 v[130:133], v[162:165], v[190:193], v[130:133]
	v_mfma_f32_16x16x32_bf16 v[146:149], v[162:165], v[206:209], v[146:149]
	ds_read_b128 v[162:165], v234 offset:4096
	s_waitcnt lgkmcnt(0)
	v_mfma_f32_16x16x32_bf16 v[134:137], v[162:165], v[178:181], v[246:249]
	v_mfma_f32_16x16x32_bf16 v[150:153], v[162:165], v[194:197], v[250:253]
	ds_read_b128 v[162:165], v235 offset:4096
	s_waitcnt lgkmcnt(0)
	v_mfma_f32_16x16x32_bf16 v[134:137], v[162:165], v[182:185], v[134:137]
	v_mfma_f32_16x16x32_bf16 v[150:153], v[162:165], v[198:201], v[150:153]
	ds_read_b128 v[162:165], v236 offset:4096
	s_waitcnt lgkmcnt(0)
	v_mfma_f32_16x16x32_bf16 v[134:137], v[162:165], v[186:189], v[134:137]
	v_mfma_f32_16x16x32_bf16 v[150:153], v[162:165], v[202:205], v[150:153]
	ds_read_b128 v[162:165], v237 offset:4096
	s_waitcnt lgkmcnt(0)
	v_mfma_f32_16x16x32_bf16 v[134:137], v[162:165], v[190:193], v[134:137]
	v_mfma_f32_16x16x32_bf16 v[150:153], v[162:165], v[206:209], v[150:153]
	ds_read_b128 v[162:165], v234 offset:8192
	s_waitcnt lgkmcnt(0)
	v_mfma_f32_16x16x32_bf16 v[138:141], v[162:165], v[178:181], v[246:249]
	v_mfma_f32_16x16x32_bf16 v[154:157], v[162:165], v[194:197], v[250:253]
	ds_read_b128 v[162:165], v235 offset:8192
	s_waitcnt lgkmcnt(0)
	v_mfma_f32_16x16x32_bf16 v[138:141], v[162:165], v[182:185], v[138:141]
	v_mfma_f32_16x16x32_bf16 v[154:157], v[162:165], v[198:201], v[154:157]
	ds_read_b128 v[162:165], v236 offset:8192
	s_waitcnt lgkmcnt(0)
	v_mfma_f32_16x16x32_bf16 v[138:141], v[162:165], v[186:189], v[138:141]
	v_mfma_f32_16x16x32_bf16 v[154:157], v[162:165], v[202:205], v[154:157]
	ds_read_b128 v[162:165], v237 offset:8192
	s_waitcnt lgkmcnt(0)
	v_mfma_f32_16x16x32_bf16 v[138:141], v[162:165], v[190:193], v[138:141]
	v_mfma_f32_16x16x32_bf16 v[154:157], v[162:165], v[206:209], v[154:157]
	ds_read_b128 v[162:165], v234 offset:12288
	s_waitcnt lgkmcnt(0)
	v_mfma_f32_16x16x32_bf16 v[142:145], v[162:165], v[178:181], v[246:249]
	v_mfma_f32_16x16x32_bf16 v[158:161], v[162:165], v[194:197], v[250:253]
	ds_read_b128 v[162:165], v235 offset:12288
	s_waitcnt lgkmcnt(0)
	v_mfma_f32_16x16x32_bf16 v[142:145], v[162:165], v[182:185], v[142:145]
	v_mfma_f32_16x16x32_bf16 v[158:161], v[162:165], v[198:201], v[158:161]
	ds_read_b128 v[162:165], v236 offset:12288
	s_waitcnt lgkmcnt(0)
	v_mfma_f32_16x16x32_bf16 v[142:145], v[162:165], v[186:189], v[142:145]
	v_mfma_f32_16x16x32_bf16 v[158:161], v[162:165], v[202:205], v[158:161]
	ds_read_b128 v[162:165], v237 offset:12288
	s_waitcnt lgkmcnt(0)
	v_mfma_f32_16x16x32_bf16 v[142:145], v[162:165], v[190:193], v[142:145]
	v_mfma_f32_16x16x32_bf16 v[158:161], v[162:165], v[206:209], v[158:161]
	ds_read_b64_tr_b16 v[162:163], v242 offset:0
	ds_read_b64_tr_b16 v[164:165], v242 offset:8192
	ds_read_b64_tr_b16 v[166:167], v242 offset:16384
	ds_read_b64_tr_b16 v[168:169], v242 offset:24576
	ds_read_b64_tr_b16 v[170:171], v242 offset:256
	ds_read_b64_tr_b16 v[172:173], v242 offset:8448
	ds_read_b64_tr_b16 v[174:175], v242 offset:16640
	ds_read_b64_tr_b16 v[176:177], v242 offset:24832
	s_nop 7
	s_branch .Lat_dt_a
.Lat_max_a:
	v_max3_f32 v238, v130, v131, v132
	v_max3_f32 v239, v146, v147, v148
	v_max3_f32 v238, v238, v133, v134
	v_max3_f32 v239, v239, v149, v150
	v_max3_f32 v238, v238, v135, v136
	v_max3_f32 v239, v239, v151, v152
	v_max3_f32 v238, v238, v137, v138
	v_max3_f32 v239, v239, v153, v154
	v_max3_f32 v238, v238, v139, v140
	v_max3_f32 v239, v239, v155, v156
	v_max3_f32 v238, v238, v141, v142
	v_max3_f32 v239, v239, v157, v158
	v_max3_f32 v238, v238, v143, v144
	v_max3_f32 v239, v239, v159, v160
	v_max_f32_e32 v238, v238, v145
	v_max_f32_e32 v239, v239, v161
	s_mov_b32 s84, 0
